# cooperative grid sync spin polls every 16 sleep quanta instead of 1 (less traffic on the single counter word)
# speedup vs baseline: 1.0083x; 1.0083x over previous
; __global__ void __launch_bounds__(512, 2) fwd_kernel(Args args) {
;     ...
;     cg::this_grid().sync();
.LBB0_92:
	s_sleep 16
	global_load_dword v2, v0, s[4:5] offset:32 sc1
	s_waitcnt vmcnt(0)
	v_and_b32_e32 v2, 0xffff0000, v2
	v_cmp_ne_u32_e32 vcc, v2, v1
	s_or_b64 s[8:9], vcc, s[8:9]
	s_andn2_b64 exec, exec, s[8:9]
	s_cbranch_execnz .LBB0_92
